# modnorm: forget-gate biases preloaded once per phase (were 4 serialized load+vmcnt(0) per row pair, which also drained the next pair's prefetch)
# speedup vs baseline: 1.0039x; 1.0039x over previous
.LBB0_299:
	s_or_b64 exec, exec, s[0:1]
	v_readlane_b32 s0, v252, 45
	v_readlane_b32 s1, v252, 46
	s_andn2_b64 vcc, exec, s[0:1]
	s_cbranch_vccnz .LBB0_318
	v_cmp_lt_i32_e32 vcc, v232, v231
	s_and_b64 s[0:1], s[92:93], exec
	v_readlane_b32 s0, v251, 17
	v_cndmask_b32_e32 v0, v228, v232, vcc
	v_cmp_lt_i32_e32 vcc, v233, v231
	v_lshlrev_b32_e32 v245, 2, v0
	s_cselect_b32 s1, 0, s0
	v_cndmask_b32_e32 v0, v228, v233, vcc
	v_cmp_lt_i32_e32 vcc, v234, v231
	v_lshlrev_b32_e32 v246, 2, v0
	v_readlane_b32 s0, v251, 16
	v_cndmask_b32_e32 v0, v228, v234, vcc
	v_cmp_lt_i32_e32 vcc, v235, v231
	v_lshlrev_b32_e32 v247, 2, v0
	s_cselect_b32 s0, 0, s0
	v_cndmask_b32_e32 v0, v228, v235, vcc
	v_cmp_lt_i32_e32 vcc, v236, v231
	s_lshl_b32 s8, s83, 13
	s_add_i32 s9, 0, 0x14000
	s_lshl_b64 s[2:3], s[94:95], 13
	s_mov_b32 s4, s83
	s_mov_b64 s[10:11], s[94:95]
	v_readlane_b32 s80, v253, 14
	v_lshlrev_b32_e32 v248, 2, v0
	v_cndmask_b32_e32 v0, v228, v236, vcc
	v_cmp_lt_i32_e32 vcc, v237, v231
	s_add_i32 s12, s9, s8
	v_readlane_b32 s83, v253, 17
	v_readlane_b32 s84, v253, 18
	v_lshlrev_b32_e32 v249, 2, v0
	v_cndmask_b32_e32 v0, v228, v237, vcc
	v_readlane_b32 s85, v253, 19
	s_mov_b32 s83, s4
	s_add_u32 s4, s84, s2
	v_lshlrev_b32_e32 v250, 2, v0
	v_lshlrev_b32_e32 v0, 12, v244
	v_ashrrev_i32_e32 v201, 31, v200
	s_addc_u32 s5, s85, s3
	s_lshl_b32 s2, s10, 4
	v_and_b32_e32 v3, 0x1000, v0
	v_lshlrev_b64 v[0:1], 2, v[200:201]
	s_ashr_i32 s3, s2, 31
	v_readlane_b32 s16, v251, 4
	v_lshlrev_b32_e32 v162, 3, v244
	v_mov_b32_e32 v163, v193
	v_lshl_add_u64 v[168:169], s[4:5], 0, v[0:1]
	s_mov_b64 s[4:5], 0x1000
	s_lshl_b64 s[2:3], s[2:3], 2
	v_readlane_b32 s20, v251, 8
	v_lshl_add_u64 v[164:165], s[0:1], 0, v[162:163]
	v_readlane_b32 s0, v253, 0
	v_lshl_add_u64 v[170:171], v[168:169], 0, s[4:5]
	s_mov_b64 s[4:5], 0x1800
	v_readlane_b32 s81, v253, 15
	v_readlane_b32 s21, v251, 9
	s_add_u32 s6, s20, s2
	v_lshlrev_b32_e32 v192, 4, v244
	v_readlane_b32 s1, v253, 1
	v_lshl_add_u64 v[172:173], v[168:169], 0, s[4:5]
	v_readlane_b32 s4, v251, 24
	v_lshrrev_b32_e32 v2, 4, v244
	v_readlane_b32 s90, v253, 24
	v_readlane_b32 s91, v253, 25
	s_addc_u32 s7, s21, s3
	v_lshl_add_u64 v[160:161], s[80:81], 0, v[192:193]
	v_lshl_add_u64 v[166:167], s[0:1], 0, v[162:163]
	v_add_u32_e32 v163, 0, v192
	v_and_b32_e32 v4, 48, v200
	v_and_b32_e32 v192, 48, v244
	v_readlane_b32 s5, v251, 25
	v_and_b32_e32 v195, 15, v200
	v_readlane_b32 s88, v253, 22
	v_readlane_b32 s89, v253, 23
	s_mov_b32 s90, 0xfffe0000
	v_lshl_add_u64 v[174:175], s[6:7], 0, v[192:193]
	global_load_dword v194, v[174:175], off
	global_load_dword v238, v[174:175], off offset:4
	global_load_dword v242, v[174:175], off offset:8
	global_load_dword v243, v[174:175], off offset:12
	v_lshlrev_b32_e32 v192, 16, v2
	v_lshl_add_u64 v[182:183], s[4:5], 0, v[0:1]
	v_or3_b32 v0, s8, v3, v4
	s_mov_b32 s91, -1
	s_mov_b64 s[88:89], 0x40000
	s_lshl_b64 s[2:3], s[10:11], 2
	s_lshl_b32 s13, s83, 3
	v_lshl_add_u32 v227, v195, 12, 0
	v_cmp_gt_u32_e64 s[0:1], 2, v195
	v_lshl_add_u32 v230, v200, 2, 0
	v_or_b32_e32 v176, 0x4000, v192
	v_mov_b32_e32 v177, v193
	v_or_b32_e32 v178, 0x8000, v192
	v_mov_b32_e32 v179, v193
	v_or_b32_e32 v180, 0xc000, v192
	v_mov_b32_e32 v181, v193
	v_or_b32_e32 v196, 60, v2
	v_add_u32_e32 v197, s9, v0
	s_mov_b32 s14, s33
	v_readlane_b32 s82, v253, 16
	v_readlane_b32 s86, v253, 20
	v_readlane_b32 s87, v253, 21
	v_readlane_b32 s92, v253, 26
	v_readlane_b32 s93, v253, 27
	v_readlane_b32 s94, v253, 28
	v_readlane_b32 s95, v253, 29
	v_readlane_b32 s17, v251, 5
	v_readlane_b32 s18, v251, 6
	v_readlane_b32 s19, v251, 7
	v_readlane_b32 s22, v251, 10
	v_readlane_b32 s23, v251, 11
	s_branch .LBB0_302

.LBB0_315:
	s_nop 1
	v_subrev_u32_e32 v36, 60, v73
	v_subrev_u32_e32 v56, 56, v73
	v_subrev_u32_e32 v64, 52, v73
	v_subrev_u32_e32 v74, 48, v73
	v_xor_b32_e32 v36, v36, v195
	v_xor_b32_e32 v56, v56, v195
	v_xor_b32_e32 v64, v64, v195
	v_xor_b32_e32 v74, v74, v195
	v_lshl_add_u32 v36, v36, 4, v227
	v_lshl_add_u32 v56, v56, 4, v227
	v_lshl_add_u32 v64, v64, 4, v227
	v_lshl_add_u32 v74, v74, 4, v227
	ds_read_b128 v[36:39], v36 offset:16384
	ds_read_b128 v[52:55], v72
	ds_read_b128 v[56:59], v56 offset:16384
	ds_read_b128 v[60:63], v72 offset:64
	ds_read_b128 v[64:67], v64 offset:16384
	ds_read_b128 v[68:71], v72 offset:128
	ds_read_b128 v[74:77], v74 offset:16384
	ds_read_b128 v[78:81], v72 offset:192
	s_waitcnt lgkmcnt(6)
	v_mfma_f32_16x16x32_bf16 v[36:39], v[36:39], v[52:55], v[44:47]
	s_add_i32 s4, s4, 16
	s_cmp_gt_u32 s4, 59
	s_waitcnt lgkmcnt(4)
	v_mfma_f32_16x16x32_bf16 v[40:43], v[56:59], v[60:63], v[40:43]
	v_subrev_u32_e32 v56, 40, v73
	v_xor_b32_e32 v56, v56, v195
	v_lshl_add_u32 v56, v56, 4, v227
	s_waitcnt lgkmcnt(2)
	v_mfma_f32_16x16x32_bf16 v[44:47], v[64:67], v[68:71], v[48:51]
	v_subrev_u32_e32 v64, 36, v73
	v_xor_b32_e32 v64, v64, v195
	v_lshl_add_u32 v64, v64, 4, v227
	s_waitcnt lgkmcnt(0)
	v_mfma_f32_16x16x32_bf16 v[32:35], v[74:77], v[78:81], v[32:35]
	v_subrev_u32_e32 v48, 44, v73
	v_subrev_u32_e32 v74, 32, v73
	v_xor_b32_e32 v48, v48, v195
	v_xor_b32_e32 v74, v74, v195
	v_lshl_add_u32 v48, v48, 4, v227
	v_lshl_add_u32 v74, v74, 4, v227
	ds_read_b128 v[48:51], v48 offset:16384
	ds_read_b128 v[52:55], v72 offset:256
	ds_read_b128 v[56:59], v56 offset:16384
	ds_read_b128 v[60:63], v72 offset:320
	ds_read_b128 v[64:67], v64 offset:16384
	ds_read_b128 v[68:71], v72 offset:384
	ds_read_b128 v[74:77], v74 offset:16384
	ds_read_b128 v[78:81], v72 offset:448
	s_waitcnt lgkmcnt(6)
	v_mfma_f32_16x16x32_bf16 v[36:39], v[48:51], v[52:55], v[36:39]
	s_waitcnt lgkmcnt(4)
	v_mfma_f32_16x16x32_bf16 v[40:43], v[56:59], v[60:63], v[40:43]
	v_subrev_u32_e32 v56, 24, v73
	v_xor_b32_e32 v56, v56, v195
	v_lshl_add_u32 v56, v56, 4, v227
	s_waitcnt lgkmcnt(2)
	v_mfma_f32_16x16x32_bf16 v[48:51], v[64:67], v[68:71], v[44:47]
	v_subrev_u32_e32 v64, 20, v73
	v_xor_b32_e32 v64, v64, v195
	v_lshl_add_u32 v64, v64, 4, v227
	s_waitcnt lgkmcnt(0)
	v_mfma_f32_16x16x32_bf16 v[52:55], v[74:77], v[78:81], v[32:35]
	v_add_u32_e32 v74, -16, v73
	v_xor_b32_e32 v74, v74, v195
	v_lshl_add_u32 v74, v74, 4, v227
	v_subrev_u32_e32 v32, 28, v73
	v_xor_b32_e32 v32, v32, v195
	v_lshl_add_u32 v32, v32, 4, v227
	ds_read_b128 v[32:35], v32 offset:16384
	ds_read_b128 v[44:47], v72 offset:512
	ds_read_b128 v[56:59], v56 offset:16384
	ds_read_b128 v[60:63], v72 offset:576
	ds_read_b128 v[64:67], v64 offset:16384
	ds_read_b128 v[68:71], v72 offset:640
	ds_read_b128 v[74:77], v74 offset:16384
	ds_read_b128 v[78:81], v72 offset:704
	s_waitcnt lgkmcnt(6)
	v_mfma_f32_16x16x32_bf16 v[44:47], v[32:35], v[44:47], v[36:39]
	s_waitcnt lgkmcnt(4)
	v_mfma_f32_16x16x32_bf16 v[40:43], v[56:59], v[60:63], v[40:43]
	v_add_u32_e32 v56, -8, v73
	v_add_u32_e32 v60, -4, v73
	v_xor_b32_e32 v56, v56, v195
	s_waitcnt lgkmcnt(2)
	v_mfma_f32_16x16x32_bf16 v[32:35], v[64:67], v[68:71], v[48:51]
	v_xor_b32_e32 v60, v60, v195
	v_lshl_add_u32 v56, v56, 4, v227
	v_lshl_add_u32 v60, v60, 4, v227
	v_add_u32_e32 v48, -12, v73
	s_waitcnt lgkmcnt(0)
	v_mfma_f32_16x16x32_bf16 v[36:39], v[74:77], v[78:81], v[52:55]
	v_xor_b32_e32 v48, v48, v195
	v_xor_b32_e32 v74, v73, v195
	v_lshl_add_u32 v48, v48, 4, v227
	v_lshl_add_u32 v74, v74, 4, v227
	ds_read_b128 v[48:51], v48 offset:16384
	ds_read_b128 v[52:55], v72 offset:768
	ds_read_b128 v[56:59], v56 offset:16384
	ds_read_b128 v[68:71], v72 offset:832
	ds_read_b128 v[60:63], v60 offset:16384
	ds_read_b128 v[64:67], v72 offset:896
	ds_read_b128 v[74:77], v74 offset:16384
	ds_read_b128 v[78:81], v72 offset:960
	s_waitcnt lgkmcnt(6)
	v_mfma_f32_16x16x32_bf16 v[44:47], v[48:51], v[52:55], v[44:47]
	v_add_u32_e32 v73, 64, v73
	v_add_u32_e32 v72, 0x400, v72
	s_waitcnt lgkmcnt(4)
	v_mfma_f32_16x16x32_bf16 v[40:43], v[56:59], v[68:71], v[40:43]
	s_waitcnt lgkmcnt(2)
	v_mfma_f32_16x16x32_bf16 v[48:51], v[60:63], v[64:67], v[32:35]
	s_waitcnt lgkmcnt(0)
	v_mfma_f32_16x16x32_bf16 v[32:35], v[74:77], v[78:81], v[36:39]
	s_cbranch_scc0 .LBB0_315
	s_and_saveexec_b64 s[4:5], s[0:1]
	s_cbranch_execz .LBB0_305
	s_nop 0
	v_pk_add_f32 v[36:37], v[46:47], v[42:43]
	v_pk_add_f32 v[38:39], v[44:45], v[40:41]
	s_nop 1
	v_pk_add_f32 v[34:35], v[50:51], v[34:35]
	v_pk_add_f32 v[32:33], v[48:49], v[32:33]
	v_pk_add_f32 v[34:35], v[36:37], v[34:35]
	v_pk_add_f32 v[36:37], v[38:39], v[32:33]
	v_or_b32_e32 v38, s8, v195
	v_ashrrev_i32_e32 v32, 31, v38
	v_lshrrev_b32_e32 v32, 20, v32
	v_add_u32_e32 v32, v38, v32
	v_ashrrev_i32_e32 v32, 12, v32
	v_ashrrev_i32_e32 v33, 31, v32
	v_mul_i32_i24_e32 v39, 0x1000, v32
	v_sub_u32_e32 v38, v38, v39
	v_lshlrev_b64 v[32:33], 18, v[32:33]
	v_ashrrev_i32_e32 v39, 31, v38
	v_lshl_add_u64 v[32:33], s[30:31], 0, v[32:33]
	v_lshl_add_u64 v[32:33], v[38:39], 2, v[32:33]
	v_add_f32_e32 v36, v36, v194
	v_mul_f32_e64 v38, |v36|, s54
	v_fma_f32 v39, |v36|, s54, -v38
	v_rndne_f32_e32 v41, v38
	v_fma_f32 v39, |v36|, s67, v39
	v_sub_f32_e32 v38, v38, v41
	v_add_f32_e32 v38, v38, v39
	v_exp_f32_e32 v38, v38
	v_cvt_i32_f32_e32 v39, v41
	v_cmp_ngt_f32_e64 vcc, |v36|, s69
	v_min_f32_e32 v40, 0, v36
	v_ldexp_f32 v38, v38, v39
	v_cndmask_b32_e32 v38, 0, v38, vcc
	v_cmp_nlt_f32_e64 vcc, |v36|, s73
	s_nop 1
	v_cndmask_b32_e32 v36, v241, v38, vcc
	v_add_f32_e32 v41, 1.0, v36
	v_add_f32_e32 v38, -1.0, v41
	v_sub_f32_e32 v39, v38, v41
	v_add_f32_e32 v39, 1.0, v39
	v_sub_f32_e32 v38, v36, v38
	v_add_f32_e32 v42, v38, v39
	v_frexp_mant_f32_e32 v38, v41
	v_cmp_gt_f32_e32 vcc, s77, v38
	v_cvt_f64_f32_e32 v[38:39], v41
	v_frexp_exp_i32_f64_e32 v38, v[38:39]
	v_subbrev_co_u32_e32 v38, vcc, 0, v38, vcc
	v_sub_u32_e32 v39, 0, v38
	v_ldexp_f32 v41, v41, v39
	v_ldexp_f32 v39, v42, v39
	v_add_f32_e32 v42, -1.0, v41
	v_add_f32_e32 v43, 1.0, v42
	v_sub_f32_e32 v43, v41, v43
	v_add_f32_e32 v43, v39, v43
	v_add_f32_e32 v44, v42, v43
	v_sub_f32_e32 v42, v42, v44
	v_add_f32_e32 v42, v43, v42
	v_add_f32_e32 v43, 1.0, v41
	v_add_f32_e32 v45, -1.0, v43
	v_sub_f32_e32 v41, v41, v45
	v_add_f32_e32 v39, v39, v41
	v_add_f32_e32 v41, v43, v39
	v_sub_f32_e32 v43, v43, v41
	v_add_f32_e32 v39, v39, v43
	v_rcp_f32_e32 v43, v41
	v_cvt_f32_i32_e32 v38, v38
	v_cmp_neq_f32_e32 vcc, s75, v36
	v_mul_f32_e32 v45, v44, v43
	v_mul_f32_e32 v46, v41, v45
	v_fma_f32 v47, v45, v41, -v46
	v_fmac_f32_e32 v47, v45, v39
	v_add_f32_e32 v48, v46, v47
	v_sub_f32_e32 v49, v44, v48
	v_sub_f32_e32 v44, v44, v49
	v_sub_f32_e32 v46, v48, v46
	v_sub_f32_e32 v44, v44, v48
	v_add_f32_e32 v42, v42, v44
	v_sub_f32_e32 v44, v46, v47
	v_add_f32_e32 v42, v44, v42
	v_add_f32_e32 v44, v49, v42
	v_mul_f32_e32 v46, v43, v44
	v_mul_f32_e32 v47, v41, v46
	v_fma_f32 v41, v46, v41, -v47
	v_fmac_f32_e32 v41, v46, v39
	v_sub_f32_e32 v39, v49, v44
	v_add_f32_e32 v39, v42, v39
	v_add_f32_e32 v42, v47, v41
	v_sub_f32_e32 v48, v44, v42
	v_sub_f32_e32 v44, v44, v48
	v_sub_f32_e32 v47, v42, v47
	v_sub_f32_e32 v42, v44, v42
	v_add_f32_e32 v39, v39, v42
	v_sub_f32_e32 v41, v47, v41
	v_add_f32_e32 v39, v41, v39
	v_add_f32_e32 v41, v45, v46
	v_add_f32_e32 v39, v48, v39
	v_sub_f32_e32 v42, v41, v45
	v_mul_f32_e32 v39, v43, v39
	v_sub_f32_e32 v42, v46, v42
	v_add_f32_e32 v39, v42, v39
	v_mul_f32_e32 v45, 0x3f317218, v38
	v_add_f32_e32 v42, v41, v39
	v_fma_f32 v46, v38, s35, -v45
	v_mul_f32_e32 v43, v42, v42
	v_fmac_f32_e32 v46, 0xb102e308, v38
	v_sub_f32_e32 v38, v42, v41
	v_fmamk_f32 v44, v43, 0x3e9b6dac, v229
	v_sub_f32_e32 v38, v39, v38
	v_add_f32_e32 v39, v45, v46
	v_fmaak_f32 v44, v43, v44, 0x3f2aaada
	v_sub_f32_e32 v41, v39, v45
	v_ldexp_f32 v45, v42, 1
	v_mul_f32_e32 v42, v42, v43
	v_mul_f32_e32 v42, v42, v44
	v_add_f32_e32 v43, v45, v42
	v_sub_f32_e32 v44, v43, v45
	v_ldexp_f32 v38, v38, 1
	v_sub_f32_e32 v42, v42, v44
	v_add_f32_e32 v38, v38, v42
	v_add_f32_e32 v42, v43, v38
	v_sub_f32_e32 v43, v42, v43
	v_sub_f32_e32 v38, v38, v43
	v_add_f32_e32 v43, v39, v42
	v_sub_f32_e32 v44, v43, v39
	v_sub_f32_e32 v45, v43, v44
	v_sub_f32_e32 v41, v46, v41
	v_sub_f32_e32 v39, v39, v45
	v_sub_f32_e32 v42, v42, v44
	v_add_f32_e32 v39, v42, v39
	v_add_f32_e32 v42, v41, v38
	v_sub_f32_e32 v44, v42, v41
	v_sub_f32_e32 v45, v42, v44
	v_sub_f32_e32 v41, v41, v45
	v_sub_f32_e32 v38, v38, v44
	v_add_f32_e32 v39, v42, v39
	v_add_f32_e32 v38, v38, v41
	v_add_f32_e32 v41, v43, v39
	v_sub_f32_e32 v42, v41, v43
	v_sub_f32_e32 v39, v39, v42
	v_add_f32_e32 v38, v38, v39
	v_add_f32_e32 v38, v41, v38
	v_cndmask_b32_e32 v38, v241, v38, vcc
	v_cmp_lt_f32_e64 vcc, |v36|, s51
	s_nop 1
	v_cndmask_b32_e32 v36, v38, v36, vcc
	v_sub_f32_e32 v36, v40, v36
	v_lshl_add_u64 v[38:39], v[32:33], 0, v[192:193]
	global_store_dword v[38:39], v36, off
	v_add_f32_e32 v36, v37, v238
	v_mul_f32_e64 v37, |v36|, s54
	v_fma_f32 v39, |v36|, s54, -v37
	v_rndne_f32_e32 v40, v37
	v_fma_f32 v39, |v36|, s67, v39
	v_sub_f32_e32 v37, v37, v40
	v_add_f32_e32 v37, v37, v39
	v_exp_f32_e32 v37, v37
	v_cvt_i32_f32_e32 v39, v40
	v_cmp_ngt_f32_e64 vcc, |v36|, s69
	v_min_f32_e32 v38, 0, v36
	v_ldexp_f32 v37, v37, v39
	v_cndmask_b32_e32 v37, 0, v37, vcc
	v_cmp_nlt_f32_e64 vcc, |v36|, s73
	s_nop 1
	v_cndmask_b32_e32 v39, v241, v37, vcc
	v_add_f32_e32 v40, 1.0, v39
	v_add_f32_e32 v36, -1.0, v40
	v_sub_f32_e32 v37, v36, v40
	v_add_f32_e32 v37, 1.0, v37
	v_sub_f32_e32 v36, v39, v36
	v_add_f32_e32 v41, v36, v37
	v_frexp_mant_f32_e32 v36, v40
	v_cmp_gt_f32_e32 vcc, s77, v36
	v_cvt_f64_f32_e32 v[36:37], v40
	v_frexp_exp_i32_f64_e32 v36, v[36:37]
	v_subbrev_co_u32_e32 v36, vcc, 0, v36, vcc
	v_sub_u32_e32 v37, 0, v36
	v_ldexp_f32 v40, v40, v37
	v_ldexp_f32 v37, v41, v37
	v_add_f32_e32 v41, -1.0, v40
	v_add_f32_e32 v42, 1.0, v41
	v_sub_f32_e32 v42, v40, v42
	v_add_f32_e32 v42, v37, v42
	v_add_f32_e32 v43, v41, v42
	v_sub_f32_e32 v41, v41, v43
	v_add_f32_e32 v41, v42, v41
	v_add_f32_e32 v42, 1.0, v40
	v_add_f32_e32 v44, -1.0, v42
	v_sub_f32_e32 v40, v40, v44
	v_add_f32_e32 v37, v37, v40
	v_add_f32_e32 v40, v42, v37
	v_sub_f32_e32 v42, v42, v40
	v_add_f32_e32 v37, v37, v42
	v_rcp_f32_e32 v42, v40
	v_cvt_f32_i32_e32 v36, v36
	v_cmp_neq_f32_e32 vcc, s75, v39
	v_mul_f32_e32 v44, v43, v42
	v_mul_f32_e32 v45, v40, v44
	v_fma_f32 v46, v44, v40, -v45
	v_fmac_f32_e32 v46, v44, v37
	v_add_f32_e32 v47, v45, v46
	v_sub_f32_e32 v48, v43, v47
	v_sub_f32_e32 v43, v43, v48
	v_sub_f32_e32 v45, v47, v45
	v_sub_f32_e32 v43, v43, v47
	v_add_f32_e32 v41, v41, v43
	v_sub_f32_e32 v43, v45, v46
	v_add_f32_e32 v41, v43, v41
	v_add_f32_e32 v43, v48, v41
	v_mul_f32_e32 v45, v42, v43
	v_mul_f32_e32 v46, v40, v45
	v_fma_f32 v40, v45, v40, -v46
	v_fmac_f32_e32 v40, v45, v37
	v_sub_f32_e32 v37, v48, v43
	v_add_f32_e32 v37, v41, v37
	v_add_f32_e32 v41, v46, v40
	v_sub_f32_e32 v47, v43, v41
	v_sub_f32_e32 v43, v43, v47
	v_sub_f32_e32 v46, v41, v46
	v_sub_f32_e32 v41, v43, v41
	v_add_f32_e32 v37, v37, v41
	v_sub_f32_e32 v40, v46, v40
	v_add_f32_e32 v37, v40, v37
	v_add_f32_e32 v40, v44, v45
	v_add_f32_e32 v37, v47, v37
	v_sub_f32_e32 v41, v40, v44
	v_mul_f32_e32 v37, v42, v37
	v_sub_f32_e32 v41, v45, v41
	v_add_f32_e32 v37, v41, v37
	v_mul_f32_e32 v44, 0x3f317218, v36
	v_add_f32_e32 v41, v40, v37
	v_fma_f32 v45, v36, s35, -v44
	v_mul_f32_e32 v42, v41, v41
	v_fmac_f32_e32 v45, 0xb102e308, v36
	v_sub_f32_e32 v36, v41, v40
	v_fmamk_f32 v43, v42, 0x3e9b6dac, v229
	v_sub_f32_e32 v36, v37, v36
	v_add_f32_e32 v37, v44, v45
	v_fmaak_f32 v43, v42, v43, 0x3f2aaada
	v_sub_f32_e32 v40, v37, v44
	v_ldexp_f32 v44, v41, 1
	v_mul_f32_e32 v41, v41, v42
	v_mul_f32_e32 v41, v41, v43
	v_add_f32_e32 v42, v44, v41
	v_sub_f32_e32 v43, v42, v44
	v_ldexp_f32 v36, v36, 1
	v_sub_f32_e32 v41, v41, v43
	v_add_f32_e32 v36, v36, v41
	v_add_f32_e32 v41, v42, v36
	v_sub_f32_e32 v42, v41, v42
	v_sub_f32_e32 v36, v36, v42
	v_add_f32_e32 v42, v37, v41
	v_sub_f32_e32 v43, v42, v37
	v_sub_f32_e32 v44, v42, v43
	v_sub_f32_e32 v40, v45, v40
	v_sub_f32_e32 v37, v37, v44
	v_sub_f32_e32 v41, v41, v43
	v_add_f32_e32 v37, v41, v37
	v_add_f32_e32 v41, v40, v36
	v_sub_f32_e32 v43, v41, v40
	v_sub_f32_e32 v44, v41, v43
	v_sub_f32_e32 v40, v40, v44
	v_sub_f32_e32 v36, v36, v43
	v_add_f32_e32 v37, v41, v37
	v_add_f32_e32 v36, v36, v40
	v_add_f32_e32 v40, v42, v37
	v_sub_f32_e32 v41, v40, v42
	v_sub_f32_e32 v37, v37, v41
	v_add_f32_e32 v36, v36, v37
	v_add_f32_e32 v36, v40, v36
	v_cndmask_b32_e32 v36, v241, v36, vcc
	v_cmp_lt_f32_e64 vcc, |v39|, s51
	s_nop 1
	v_cndmask_b32_e32 v36, v36, v39, vcc
	v_sub_f32_e32 v38, v38, v36
	v_lshl_add_u64 v[36:37], v[32:33], 0, v[176:177]
	global_store_dword v[36:37], v38, off
	v_add_f32_e32 v34, v34, v242
	v_mul_f32_e64 v36, |v34|, s54
	v_fma_f32 v37, |v34|, s54, -v36
	v_rndne_f32_e32 v39, v36
	v_fma_f32 v37, |v34|, s67, v37
	v_sub_f32_e32 v36, v36, v39
	v_add_f32_e32 v36, v36, v37
	v_exp_f32_e32 v36, v36
	v_cvt_i32_f32_e32 v37, v39
	v_cmp_ngt_f32_e64 vcc, |v34|, s69
	v_min_f32_e32 v38, 0, v34
	v_ldexp_f32 v36, v36, v37
	v_cndmask_b32_e32 v36, 0, v36, vcc
	v_cmp_nlt_f32_e64 vcc, |v34|, s73
	s_nop 1
	v_cndmask_b32_e32 v34, v241, v36, vcc
	v_add_f32_e32 v39, 1.0, v34
	v_add_f32_e32 v36, -1.0, v39
	v_sub_f32_e32 v37, v36, v39
	v_add_f32_e32 v37, 1.0, v37
	v_sub_f32_e32 v36, v34, v36
	v_add_f32_e32 v40, v36, v37
	v_frexp_mant_f32_e32 v36, v39
	v_cmp_gt_f32_e32 vcc, s77, v36
	v_cvt_f64_f32_e32 v[36:37], v39
	v_frexp_exp_i32_f64_e32 v36, v[36:37]
	v_subbrev_co_u32_e32 v36, vcc, 0, v36, vcc
	v_sub_u32_e32 v37, 0, v36
	v_ldexp_f32 v39, v39, v37
	v_ldexp_f32 v37, v40, v37
	v_add_f32_e32 v40, -1.0, v39
	v_add_f32_e32 v41, 1.0, v40
	v_sub_f32_e32 v41, v39, v41
	v_add_f32_e32 v41, v37, v41
	v_add_f32_e32 v42, v40, v41
	v_sub_f32_e32 v40, v40, v42
	v_add_f32_e32 v40, v41, v40
	v_add_f32_e32 v41, 1.0, v39
	v_add_f32_e32 v43, -1.0, v41
	v_sub_f32_e32 v39, v39, v43
	v_add_f32_e32 v37, v37, v39
	v_add_f32_e32 v39, v41, v37
	v_sub_f32_e32 v41, v41, v39
	v_add_f32_e32 v37, v37, v41
	v_rcp_f32_e32 v41, v39
	v_cvt_f32_i32_e32 v36, v36
	v_cmp_neq_f32_e32 vcc, s75, v34
	v_mul_f32_e32 v43, v42, v41
	v_mul_f32_e32 v44, v39, v43
	v_fma_f32 v45, v43, v39, -v44
	v_fmac_f32_e32 v45, v43, v37
	v_add_f32_e32 v46, v44, v45
	v_sub_f32_e32 v47, v42, v46
	v_sub_f32_e32 v42, v42, v47
	v_sub_f32_e32 v44, v46, v44
	v_sub_f32_e32 v42, v42, v46
	v_add_f32_e32 v40, v40, v42
	v_sub_f32_e32 v42, v44, v45
	v_add_f32_e32 v40, v42, v40
	v_add_f32_e32 v42, v47, v40
	v_mul_f32_e32 v44, v41, v42
	v_mul_f32_e32 v45, v39, v44
	v_fma_f32 v39, v44, v39, -v45
	v_fmac_f32_e32 v39, v44, v37
	v_sub_f32_e32 v37, v47, v42
	v_add_f32_e32 v37, v40, v37
	v_add_f32_e32 v40, v45, v39
	v_sub_f32_e32 v46, v42, v40
	v_sub_f32_e32 v42, v42, v46
	v_sub_f32_e32 v45, v40, v45
	v_sub_f32_e32 v40, v42, v40
	v_add_f32_e32 v37, v37, v40
	v_sub_f32_e32 v39, v45, v39
	v_add_f32_e32 v37, v39, v37
	v_add_f32_e32 v39, v43, v44
	v_add_f32_e32 v37, v46, v37
	v_sub_f32_e32 v40, v39, v43
	v_mul_f32_e32 v37, v41, v37
	v_sub_f32_e32 v40, v44, v40
	v_add_f32_e32 v37, v40, v37
	v_mul_f32_e32 v43, 0x3f317218, v36
	v_add_f32_e32 v40, v39, v37
	v_fma_f32 v44, v36, s35, -v43
	v_mul_f32_e32 v41, v40, v40
	v_fmac_f32_e32 v44, 0xb102e308, v36
	v_sub_f32_e32 v36, v40, v39
	v_fmamk_f32 v42, v41, 0x3e9b6dac, v229
	v_sub_f32_e32 v36, v37, v36
	v_add_f32_e32 v37, v43, v44
	v_fmaak_f32 v42, v41, v42, 0x3f2aaada
	v_sub_f32_e32 v39, v37, v43
	v_ldexp_f32 v43, v40, 1
	v_mul_f32_e32 v40, v40, v41
	v_mul_f32_e32 v40, v40, v42
	v_add_f32_e32 v41, v43, v40
	v_sub_f32_e32 v42, v41, v43
	v_ldexp_f32 v36, v36, 1
	v_sub_f32_e32 v40, v40, v42
	v_add_f32_e32 v36, v36, v40
	v_add_f32_e32 v40, v41, v36
	v_sub_f32_e32 v41, v40, v41
	v_sub_f32_e32 v36, v36, v41
	v_add_f32_e32 v41, v37, v40
	v_sub_f32_e32 v42, v41, v37
	v_sub_f32_e32 v43, v41, v42
	v_sub_f32_e32 v39, v44, v39
	v_sub_f32_e32 v37, v37, v43
	v_sub_f32_e32 v40, v40, v42
	v_add_f32_e32 v37, v40, v37
	v_add_f32_e32 v40, v39, v36
	v_sub_f32_e32 v42, v40, v39
	v_sub_f32_e32 v43, v40, v42
	v_sub_f32_e32 v39, v39, v43
	v_sub_f32_e32 v36, v36, v42
	v_add_f32_e32 v37, v40, v37
	v_add_f32_e32 v36, v36, v39
	v_add_f32_e32 v39, v41, v37
	v_sub_f32_e32 v40, v39, v41
	v_sub_f32_e32 v37, v37, v40
	v_add_f32_e32 v36, v36, v37
	v_add_f32_e32 v36, v39, v36
	v_cndmask_b32_e32 v36, v241, v36, vcc
	v_cmp_lt_f32_e64 vcc, |v34|, s51
	s_nop 1
	v_cndmask_b32_e32 v34, v36, v34, vcc
	v_sub_f32_e32 v34, v38, v34
	v_lshl_add_u64 v[36:37], v[32:33], 0, v[178:179]
	global_store_dword v[36:37], v34, off
	v_lshl_add_u64 v[32:33], v[32:33], 0, v[180:181]
	v_add_f32_e32 v35, v35, v243
	v_mul_f32_e64 v36, |v35|, s54
	v_fma_f32 v37, |v35|, s54, -v36
	v_rndne_f32_e32 v38, v36
	v_fma_f32 v37, |v35|, s67, v37
	v_sub_f32_e32 v36, v36, v38
	v_add_f32_e32 v36, v36, v37
	v_exp_f32_e32 v36, v36
	v_cvt_i32_f32_e32 v37, v38
	v_cmp_ngt_f32_e64 vcc, |v35|, s69
	v_min_f32_e32 v34, 0, v35
	v_ldexp_f32 v36, v36, v37
	v_cndmask_b32_e32 v36, 0, v36, vcc
	v_cmp_nlt_f32_e64 vcc, |v35|, s73
	s_nop 1
	v_cndmask_b32_e32 v35, v241, v36, vcc
	v_add_f32_e32 v38, 1.0, v35
	v_add_f32_e32 v36, -1.0, v38
	v_sub_f32_e32 v37, v36, v38
	v_add_f32_e32 v37, 1.0, v37
	v_sub_f32_e32 v36, v35, v36
	v_add_f32_e32 v39, v36, v37
	v_frexp_mant_f32_e32 v36, v38
	v_cmp_gt_f32_e32 vcc, s77, v36
	v_cvt_f64_f32_e32 v[36:37], v38
	v_frexp_exp_i32_f64_e32 v36, v[36:37]
	v_subbrev_co_u32_e32 v36, vcc, 0, v36, vcc
	v_sub_u32_e32 v37, 0, v36
	v_ldexp_f32 v38, v38, v37
	v_ldexp_f32 v37, v39, v37
	v_add_f32_e32 v39, -1.0, v38
	v_add_f32_e32 v40, 1.0, v39
	v_sub_f32_e32 v40, v38, v40
	v_add_f32_e32 v40, v37, v40
	v_add_f32_e32 v41, v39, v40
	v_sub_f32_e32 v39, v39, v41
	v_add_f32_e32 v39, v40, v39
	v_add_f32_e32 v40, 1.0, v38
	v_add_f32_e32 v42, -1.0, v40
	v_sub_f32_e32 v38, v38, v42
	v_add_f32_e32 v37, v37, v38
	v_add_f32_e32 v38, v40, v37
	v_sub_f32_e32 v40, v40, v38
	v_add_f32_e32 v37, v37, v40
	v_rcp_f32_e32 v40, v38
	v_cvt_f32_i32_e32 v36, v36
	v_cmp_neq_f32_e32 vcc, s75, v35
	v_mul_f32_e32 v42, v41, v40
	v_mul_f32_e32 v43, v38, v42
	v_fma_f32 v44, v42, v38, -v43
	v_fmac_f32_e32 v44, v42, v37
	v_add_f32_e32 v45, v43, v44
	v_sub_f32_e32 v46, v41, v45
	v_sub_f32_e32 v41, v41, v46
	v_sub_f32_e32 v43, v45, v43
	v_sub_f32_e32 v41, v41, v45
	v_add_f32_e32 v39, v39, v41
	v_sub_f32_e32 v41, v43, v44
	v_add_f32_e32 v39, v41, v39
	v_add_f32_e32 v41, v46, v39
	v_mul_f32_e32 v43, v40, v41
	v_mul_f32_e32 v44, v38, v43
	v_fma_f32 v38, v43, v38, -v44
	v_fmac_f32_e32 v38, v43, v37
	v_sub_f32_e32 v37, v46, v41
	v_add_f32_e32 v37, v39, v37
	v_add_f32_e32 v39, v44, v38
	v_sub_f32_e32 v45, v41, v39
	v_sub_f32_e32 v41, v41, v45
	v_sub_f32_e32 v44, v39, v44
	v_sub_f32_e32 v39, v41, v39
	v_add_f32_e32 v37, v37, v39
	v_sub_f32_e32 v38, v44, v38
	v_add_f32_e32 v37, v38, v37
	v_add_f32_e32 v38, v42, v43
	v_add_f32_e32 v37, v45, v37
	v_sub_f32_e32 v39, v38, v42
	v_mul_f32_e32 v37, v40, v37
	v_sub_f32_e32 v39, v43, v39
	v_add_f32_e32 v37, v39, v37
	v_mul_f32_e32 v42, 0x3f317218, v36
	v_add_f32_e32 v39, v38, v37
	v_fma_f32 v43, v36, s35, -v42
	v_mul_f32_e32 v40, v39, v39
	v_fmac_f32_e32 v43, 0xb102e308, v36
	v_sub_f32_e32 v36, v39, v38
	v_fmamk_f32 v41, v40, 0x3e9b6dac, v229
	v_sub_f32_e32 v36, v37, v36
	v_add_f32_e32 v37, v42, v43
	v_fmaak_f32 v41, v40, v41, 0x3f2aaada
	v_sub_f32_e32 v38, v37, v42
	v_ldexp_f32 v42, v39, 1
	v_mul_f32_e32 v39, v39, v40
	v_mul_f32_e32 v39, v39, v41
	v_add_f32_e32 v40, v42, v39
	v_sub_f32_e32 v41, v40, v42
	v_ldexp_f32 v36, v36, 1
	v_sub_f32_e32 v39, v39, v41
	v_add_f32_e32 v36, v36, v39
	v_add_f32_e32 v39, v40, v36
	v_sub_f32_e32 v40, v39, v40
	v_sub_f32_e32 v36, v36, v40
	v_add_f32_e32 v40, v37, v39
	v_sub_f32_e32 v41, v40, v37
	v_sub_f32_e32 v42, v40, v41
	v_sub_f32_e32 v38, v43, v38
	v_sub_f32_e32 v37, v37, v42
	v_sub_f32_e32 v39, v39, v41
	v_add_f32_e32 v37, v39, v37
	v_add_f32_e32 v39, v38, v36
	v_sub_f32_e32 v41, v39, v38
	v_sub_f32_e32 v42, v39, v41
	v_sub_f32_e32 v38, v38, v42
	v_sub_f32_e32 v36, v36, v41
	v_add_f32_e32 v37, v39, v37
	v_add_f32_e32 v36, v36, v38
	v_add_f32_e32 v38, v40, v37
	v_sub_f32_e32 v39, v38, v40
	v_sub_f32_e32 v37, v37, v39
	v_add_f32_e32 v36, v36, v37
	v_add_f32_e32 v36, v38, v36
	v_cndmask_b32_e32 v36, v241, v36, vcc
	v_cmp_lt_f32_e64 vcc, |v35|, s51
	s_nop 1
	v_cndmask_b32_e32 v35, v36, v35, vcc
	v_sub_f32_e32 v34, v34, v35
	global_store_dword v[32:33], v34, off
	s_branch .LBB0_305
.LBB0_318:
	v_mov_b32_e32 v194, 0x3a800000
	v_mov_b32_e32 v238, 0xff800000
	v_mov_b32_e32 v242, 0x30000
	v_mov_b32_e32 v243, 0x18000
	v_readlane_b32 s20, v253, 51
	v_readlane_b32 s12, v253, 44
	v_readlane_b32 s21, v253, 52
	v_readlane_b32 s18, v253, 39
	v_readlane_b32 s13, v253, 45
	v_mov_b64_e32 v[248:249], v[198:199]
	v_mov_b64_e32 v[198:199], 0x6ff
	v_readlane_b32 s19, v253, 40
	s_branch .LBB0_342
